# prologue weight transposes software-pipelined: 4 tiles of loads in flight per WG
# baseline (speedup 1.0000x reference)
.LBB0_66:
	s_cmpk_gt_i32 s20, 0x2bff
	s_cbranch_scc0 .Ltc1_win
	s_lshl_b32 s15, s20, 6
	s_lshl_b32 s17, s20, 1
	s_and_b32 s21, s15, 0x7c0
	v_add_u32_e32 v0, s21, v13
	v_ashrrev_i32_e32 v1, 31, v0
	v_lshlrev_b64 v[10:11], 13, v[0:1]
	v_add_u32_e32 v0, s21, v18
	s_and_b32 s24, s17, 0x7c0
	v_ashrrev_i32_e32 v1, 31, v0
	s_cmpk_gt_u32 s20, 0x3bff
	v_lshlrev_b64 v[14:15], 13, v[0:1]
	v_add_u32_e32 v8, s24, v20
	s_cbranch_scc0 .Ltc1_wout
	s_add_i32 s0, s20, 0xffffc400
	s_lshr_b32 s0, s0, 10
	s_lshl_b64 s[4:5], s[0:1], 24
	s_add_u32 s25, s68, s4
	s_addc_u32 s27, s69, s5
	s_lshl_b64 s[4:5], s[0:1], 23
	s_add_u32 s4, s3, s4
	s_addc_u32 s5, s6, s5
	s_branch .Ltc1_sq
.Ltc1_wout:
	s_add_i32 s0, s20, 0xffffd400
	s_lshr_b32 s0, s0, 10
	s_lshl_b64 s[4:5], s[0:1], 24
	s_add_u32 s25, s66, s4
	s_addc_u32 s27, s67, s5
	s_lshl_b64 s[4:5], s[0:1], 23
	s_add_u32 s4, s7, s4
	s_addc_u32 s5, s8, s5
.Ltc1_sq:
	s_lshl_b32 s0, s24, 2
	s_add_u32 s26, s25, s0
	s_addc_u32 s27, s27, 0
	v_mov_b32_e32 v7, v5
	v_lshl_add_u64 v[16:17], s[26:27], 0, v[6:7]
	v_lshl_add_u64 v[0:1], v[16:17], 0, v[10:11]
	global_load_dwordx4 v[80:83], v[0:1], off
	v_lshl_add_u64 v[16:17], v[16:17], 0, v[14:15]
	global_load_dwordx4 v[84:87], v[16:17], off
	v_ashrrev_i32_e32 v9, 31, v8
	v_lshlrev_b64 v[16:17], 12, v[8:9]
	v_lshl_add_u64 v[16:17], s[4:5], 0, v[16:17]
	s_lshl_b32 s0, s21, 1
	v_lshl_add_u64 v[88:89], v[16:17], 0, s[0:1]
	v_mov_b32_e32 v90, v22
	s_branch .Ltc1_done
.Ltc1_win:
	s_mul_hi_i32 s0, s20, 0x2e8ba2e9
	s_lshr_b32 s4, s0, 31
	s_ashr_i32 s0, s0, 9
	s_add_i32 s0, s0, s4
	s_mul_i32 s4, s0, 0xfffff500
	s_add_i32 s4, s20, s4
	s_bfe_u32 s5, s4, 0x5001a
	s_add_i32 s5, s4, s5
	s_sext_i32_i16 s21, s5
	s_and_b32 s5, s5, 0xffe0
	s_sub_i32 s5, s4, s5
	s_and_b32 s4, s4, 0xfffffe00
	s_sext_i32_i16 s24, s5
	s_cmpk_eq_i32 s4, 0x800
	s_mul_i32 s5, s0, 0x2c00000
	s_cselect_b64 vcc, -1, 0
	s_mul_hi_i32 s4, s0, 0x2c00000
	s_add_u32 s25, s22, s5
	s_addc_u32 s30, s23, s4
	s_mul_hi_i32 s5, s0, 0x1600000
	s_mul_i32 s0, s0, 0x1600000
	s_add_u32 s4, s9, s0
	s_addc_u32 s5, s14, s5
	s_lshl_b32 s0, s21, 1
	s_and_b32 s26, s0, 0xffffffc0
	s_ashr_i32 s27, s26, 31
	s_lshl_b32 s24, s24, 6
	s_lshl_b64 s[28:29], s[26:27], 2
	s_add_u32 s28, s25, s28
	s_addc_u32 s29, s30, s29
	v_mov_b32_e32 v7, v5
	v_lshl_add_u64 v[8:9], s[28:29], 0, v[6:7]
	v_add_u32_e32 v0, s24, v13
	v_mad_i64_i32 v[0:1], s[28:29], v0, s19, v[8:9]
	global_load_dwordx4 v[80:83], v[0:1], off
	v_add_u32_e32 v7, s24, v18
	v_mad_i64_i32 v[8:9], s[28:29], v7, s19, v[8:9]
	global_load_dwordx4 v[84:87], v[8:9], off
	v_cndmask_b32_e32 v7, v20, v23, vcc
	v_lshl_add_u32 v90, v7, 2, v21
	v_add_u32_e32 v14, s26, v20
	v_ashrrev_i32_e32 v15, 31, v14
	v_lshlrev_b64 v[14:15], 12, v[14:15]
	v_lshl_add_u64 v[14:15], s[4:5], 0, v[14:15]
	s_ashr_i32 s25, s24, 31
	v_lshl_add_u64 v[88:89], s[24:25], 1, v[14:15]
.Ltc1_done:
	s_add_i32 s20, s20, s80
	s_cmpk_gt_i32 s20, 0x2bff
	s_cbranch_scc0 .Ltc2_win
	s_lshl_b32 s15, s20, 6
	s_lshl_b32 s17, s20, 1
	s_and_b32 s21, s15, 0x7c0
	v_add_u32_e32 v0, s21, v13
	v_ashrrev_i32_e32 v1, 31, v0
	v_lshlrev_b64 v[10:11], 13, v[0:1]
	v_add_u32_e32 v0, s21, v18
	s_and_b32 s24, s17, 0x7c0
	v_ashrrev_i32_e32 v1, 31, v0
	s_cmpk_gt_u32 s20, 0x3bff
	v_lshlrev_b64 v[14:15], 13, v[0:1]
	v_add_u32_e32 v8, s24, v20
	s_cbranch_scc0 .Ltc2_wout
	s_add_i32 s0, s20, 0xffffc400
	s_lshr_b32 s0, s0, 10
	s_lshl_b64 s[4:5], s[0:1], 24
	s_add_u32 s25, s68, s4
	s_addc_u32 s27, s69, s5
	s_lshl_b64 s[4:5], s[0:1], 23
	s_add_u32 s4, s3, s4
	s_addc_u32 s5, s6, s5
	s_branch .Ltc2_sq

.Ltc2_sq:
	s_lshl_b32 s0, s24, 2
	s_add_u32 s26, s25, s0
	s_addc_u32 s27, s27, 0
	v_mov_b32_e32 v7, v5
	v_lshl_add_u64 v[16:17], s[26:27], 0, v[6:7]
	v_lshl_add_u64 v[0:1], v[16:17], 0, v[10:11]
	global_load_dwordx4 v[92:95], v[0:1], off
	v_lshl_add_u64 v[16:17], v[16:17], 0, v[14:15]
	global_load_dwordx4 v[96:99], v[16:17], off
	v_ashrrev_i32_e32 v9, 31, v8
	v_lshlrev_b64 v[16:17], 12, v[8:9]
	v_lshl_add_u64 v[16:17], s[4:5], 0, v[16:17]
	s_lshl_b32 s0, s21, 1
	v_lshl_add_u64 v[100:101], v[16:17], 0, s[0:1]
	v_mov_b32_e32 v102, v22
	s_branch .Ltc2_done
.Ltc2_win:
	s_mul_hi_i32 s0, s20, 0x2e8ba2e9
	s_lshr_b32 s4, s0, 31
	s_ashr_i32 s0, s0, 9
	s_add_i32 s0, s0, s4
	s_mul_i32 s4, s0, 0xfffff500
	s_add_i32 s4, s20, s4
	s_bfe_u32 s5, s4, 0x5001a
	s_add_i32 s5, s4, s5
	s_sext_i32_i16 s21, s5
	s_and_b32 s5, s5, 0xffe0
	s_sub_i32 s5, s4, s5
	s_and_b32 s4, s4, 0xfffffe00
	s_sext_i32_i16 s24, s5
	s_cmpk_eq_i32 s4, 0x800
	s_mul_i32 s5, s0, 0x2c00000
	s_cselect_b64 vcc, -1, 0
	s_mul_hi_i32 s4, s0, 0x2c00000
	s_add_u32 s25, s22, s5
	s_addc_u32 s30, s23, s4
	s_mul_hi_i32 s5, s0, 0x1600000
	s_mul_i32 s0, s0, 0x1600000
	s_add_u32 s4, s9, s0
	s_addc_u32 s5, s14, s5
	s_lshl_b32 s0, s21, 1
	s_and_b32 s26, s0, 0xffffffc0
	s_ashr_i32 s27, s26, 31
	s_lshl_b32 s24, s24, 6
	s_lshl_b64 s[28:29], s[26:27], 2
	s_add_u32 s28, s25, s28
	s_addc_u32 s29, s30, s29
	v_mov_b32_e32 v7, v5
	v_lshl_add_u64 v[8:9], s[28:29], 0, v[6:7]
	v_add_u32_e32 v0, s24, v13
	v_mad_i64_i32 v[0:1], s[28:29], v0, s19, v[8:9]
	global_load_dwordx4 v[92:95], v[0:1], off
	v_add_u32_e32 v7, s24, v18
	v_mad_i64_i32 v[8:9], s[28:29], v7, s19, v[8:9]
	global_load_dwordx4 v[96:99], v[8:9], off
	v_cndmask_b32_e32 v7, v20, v23, vcc
	v_lshl_add_u32 v102, v7, 2, v21
	v_add_u32_e32 v14, s26, v20
	v_ashrrev_i32_e32 v15, 31, v14
	v_lshlrev_b64 v[14:15], 12, v[14:15]
	v_lshl_add_u64 v[14:15], s[4:5], 0, v[14:15]
	s_ashr_i32 s25, s24, 31
	v_lshl_add_u64 v[100:101], s[24:25], 1, v[14:15]

.Ltc3_sq:
	s_lshl_b32 s0, s24, 2
	s_add_u32 s26, s25, s0
	s_addc_u32 s27, s27, 0
	v_mov_b32_e32 v7, v5
	v_lshl_add_u64 v[16:17], s[26:27], 0, v[6:7]
	v_lshl_add_u64 v[0:1], v[16:17], 0, v[10:11]
	global_load_dwordx4 v[104:107], v[0:1], off
	v_lshl_add_u64 v[16:17], v[16:17], 0, v[14:15]
	global_load_dwordx4 v[108:111], v[16:17], off
	v_ashrrev_i32_e32 v9, 31, v8
	v_lshlrev_b64 v[16:17], 12, v[8:9]
	v_lshl_add_u64 v[16:17], s[4:5], 0, v[16:17]
	s_lshl_b32 s0, s21, 1
	v_lshl_add_u64 v[112:113], v[16:17], 0, s[0:1]
	v_mov_b32_e32 v114, v22
	s_branch .Ltc3_done
.Ltc3_win:
	s_mul_hi_i32 s0, s20, 0x2e8ba2e9
	s_lshr_b32 s4, s0, 31
	s_ashr_i32 s0, s0, 9
	s_add_i32 s0, s0, s4
	s_mul_i32 s4, s0, 0xfffff500
	s_add_i32 s4, s20, s4
	s_bfe_u32 s5, s4, 0x5001a
	s_add_i32 s5, s4, s5
	s_sext_i32_i16 s21, s5
	s_and_b32 s5, s5, 0xffe0
	s_sub_i32 s5, s4, s5
	s_and_b32 s4, s4, 0xfffffe00
	s_sext_i32_i16 s24, s5
	s_cmpk_eq_i32 s4, 0x800
	s_mul_i32 s5, s0, 0x2c00000
	s_cselect_b64 vcc, -1, 0
	s_mul_hi_i32 s4, s0, 0x2c00000
	s_add_u32 s25, s22, s5
	s_addc_u32 s30, s23, s4
	s_mul_hi_i32 s5, s0, 0x1600000
	s_mul_i32 s0, s0, 0x1600000
	s_add_u32 s4, s9, s0
	s_addc_u32 s5, s14, s5
	s_lshl_b32 s0, s21, 1
	s_and_b32 s26, s0, 0xffffffc0
	s_ashr_i32 s27, s26, 31
	s_lshl_b32 s24, s24, 6
	s_lshl_b64 s[28:29], s[26:27], 2
	s_add_u32 s28, s25, s28
	s_addc_u32 s29, s30, s29
	v_mov_b32_e32 v7, v5
	v_lshl_add_u64 v[8:9], s[28:29], 0, v[6:7]
	v_add_u32_e32 v0, s24, v13
	v_mad_i64_i32 v[0:1], s[28:29], v0, s19, v[8:9]
	global_load_dwordx4 v[104:107], v[0:1], off
	v_add_u32_e32 v7, s24, v18
	v_mad_i64_i32 v[8:9], s[28:29], v7, s19, v[8:9]
	global_load_dwordx4 v[108:111], v[8:9], off
	v_cndmask_b32_e32 v7, v20, v23, vcc
	v_lshl_add_u32 v114, v7, 2, v21
	v_add_u32_e32 v14, s26, v20
	v_ashrrev_i32_e32 v15, 31, v14
	v_lshlrev_b64 v[14:15], 12, v[14:15]
	v_lshl_add_u64 v[14:15], s[4:5], 0, v[14:15]
	s_ashr_i32 s25, s24, 31
	v_lshl_add_u64 v[112:113], s[24:25], 1, v[14:15]

.Ltc4_sq:
	s_lshl_b32 s0, s24, 2
	s_add_u32 s26, s25, s0
	s_addc_u32 s27, s27, 0
	v_mov_b32_e32 v7, v5
	v_lshl_add_u64 v[16:17], s[26:27], 0, v[6:7]
	v_lshl_add_u64 v[0:1], v[16:17], 0, v[10:11]
	global_load_dwordx4 v[116:119], v[0:1], off
	v_lshl_add_u64 v[16:17], v[16:17], 0, v[14:15]
	global_load_dwordx4 v[120:123], v[16:17], off
	v_ashrrev_i32_e32 v9, 31, v8
	v_lshlrev_b64 v[16:17], 12, v[8:9]
	v_lshl_add_u64 v[16:17], s[4:5], 0, v[16:17]
	s_lshl_b32 s0, s21, 1
	v_lshl_add_u64 v[124:125], v[16:17], 0, s[0:1]
	v_mov_b32_e32 v126, v22
	s_branch .Ltc4_done
.Ltc4_win:
	s_mul_hi_i32 s0, s20, 0x2e8ba2e9
	s_lshr_b32 s4, s0, 31
	s_ashr_i32 s0, s0, 9
	s_add_i32 s0, s0, s4
	s_mul_i32 s4, s0, 0xfffff500
	s_add_i32 s4, s20, s4
	s_bfe_u32 s5, s4, 0x5001a
	s_add_i32 s5, s4, s5
	s_sext_i32_i16 s21, s5
	s_and_b32 s5, s5, 0xffe0
	s_sub_i32 s5, s4, s5
	s_and_b32 s4, s4, 0xfffffe00
	s_sext_i32_i16 s24, s5
	s_cmpk_eq_i32 s4, 0x800
	s_mul_i32 s5, s0, 0x2c00000
	s_cselect_b64 vcc, -1, 0
	s_mul_hi_i32 s4, s0, 0x2c00000
	s_add_u32 s25, s22, s5
	s_addc_u32 s30, s23, s4
	s_mul_hi_i32 s5, s0, 0x1600000
	s_mul_i32 s0, s0, 0x1600000
	s_add_u32 s4, s9, s0
	s_addc_u32 s5, s14, s5
	s_lshl_b32 s0, s21, 1
	s_and_b32 s26, s0, 0xffffffc0
	s_ashr_i32 s27, s26, 31
	s_lshl_b32 s24, s24, 6
	s_lshl_b64 s[28:29], s[26:27], 2
	s_add_u32 s28, s25, s28
	s_addc_u32 s29, s30, s29
	v_mov_b32_e32 v7, v5
	v_lshl_add_u64 v[8:9], s[28:29], 0, v[6:7]
	v_add_u32_e32 v0, s24, v13
	v_mad_i64_i32 v[0:1], s[28:29], v0, s19, v[8:9]
	global_load_dwordx4 v[116:119], v[0:1], off
	v_add_u32_e32 v7, s24, v18
	v_mad_i64_i32 v[8:9], s[28:29], v7, s19, v[8:9]
	global_load_dwordx4 v[120:123], v[8:9], off
	v_cndmask_b32_e32 v7, v20, v23, vcc
	v_lshl_add_u32 v126, v7, 2, v21
	v_add_u32_e32 v14, s26, v20
	v_ashrrev_i32_e32 v15, 31, v14
	v_lshlrev_b64 v[14:15], 12, v[14:15]
	v_lshl_add_u64 v[14:15], s[4:5], 0, v[14:15]
	s_ashr_i32 s25, s24, 31
	v_lshl_add_u64 v[124:125], s[24:25], 1, v[14:15]
.Ltc4_done:
	s_add_i32 s20, s20, s80
	s_waitcnt vmcnt(6)
	s_barrier
	ds_write2_b32 v24, v80, v81 offset1:1
	ds_write2_b32 v24, v82, v83 offset0:2 offset1:3
	ds_write2_b32 v25, v84, v85 offset1:1
	ds_write2_b32 v26, v86, v87 offset1:1
	v_add_u32_e32 v136, 0x400, v90
	v_lshl_add_u64 v[88:89], v[88:89], 0, v[4:5]
	s_waitcnt lgkmcnt(0)
	s_barrier
	ds_read2_b32 v[128:129], v90 offset1:65
	ds_read2_b32 v[130:131], v90 offset0:130 offset1:195
	ds_read2_b32 v[132:133], v136 offset0:4 offset1:69
	ds_read2_b32 v[134:135], v136 offset0:134 offset1:199
	s_waitcnt lgkmcnt(3)
	v_cvt_pk_bf16_f32 v128, v128, v129
	s_waitcnt lgkmcnt(2)
	v_cvt_pk_bf16_f32 v129, v130, v131
	s_waitcnt lgkmcnt(1)
	v_cvt_pk_bf16_f32 v130, v132, v133
	s_waitcnt lgkmcnt(0)
	v_cvt_pk_bf16_f32 v131, v134, v135
	global_store_dwordx4 v[88:89], v[128:131], off
	s_cmpk_gt_i32 s20, 0x2bff
	s_cbranch_scc0 .Ltc5_win
	s_lshl_b32 s15, s20, 6
	s_lshl_b32 s17, s20, 1
	s_and_b32 s21, s15, 0x7c0
	v_add_u32_e32 v0, s21, v13
	v_ashrrev_i32_e32 v1, 31, v0
	v_lshlrev_b64 v[10:11], 13, v[0:1]
	v_add_u32_e32 v0, s21, v18
	s_and_b32 s24, s17, 0x7c0
	v_ashrrev_i32_e32 v1, 31, v0
	s_cmpk_gt_u32 s20, 0x3bff
	v_lshlrev_b64 v[14:15], 13, v[0:1]
	v_add_u32_e32 v8, s24, v20
	s_cbranch_scc0 .Ltc5_wout
	s_add_i32 s0, s20, 0xffffc400
	s_lshr_b32 s0, s0, 10
	s_lshl_b64 s[4:5], s[0:1], 24
	s_add_u32 s25, s68, s4
	s_addc_u32 s27, s69, s5
	s_lshl_b64 s[4:5], s[0:1], 23
	s_add_u32 s4, s3, s4
	s_addc_u32 s5, s6, s5
	s_branch .Ltc5_sq

.Ltc5_done:
	s_add_i32 s20, s20, s80
	s_waitcnt vmcnt(7)
	s_barrier
	ds_write2_b32 v24, v92, v93 offset1:1
	ds_write2_b32 v24, v94, v95 offset0:2 offset1:3
	ds_write2_b32 v25, v96, v97 offset1:1
	ds_write2_b32 v26, v98, v99 offset1:1
	v_add_u32_e32 v136, 0x400, v102
	v_lshl_add_u64 v[100:101], v[100:101], 0, v[4:5]
	s_waitcnt lgkmcnt(0)
	s_barrier
	ds_read2_b32 v[128:129], v102 offset1:65
	ds_read2_b32 v[130:131], v102 offset0:130 offset1:195
	ds_read2_b32 v[132:133], v136 offset0:4 offset1:69
	ds_read2_b32 v[134:135], v136 offset0:134 offset1:199
	s_waitcnt lgkmcnt(3)
	v_cvt_pk_bf16_f32 v128, v128, v129
	s_waitcnt lgkmcnt(2)
	v_cvt_pk_bf16_f32 v129, v130, v131
	s_waitcnt lgkmcnt(1)
	v_cvt_pk_bf16_f32 v130, v132, v133
	s_waitcnt lgkmcnt(0)
	v_cvt_pk_bf16_f32 v131, v134, v135
	global_store_dwordx4 v[100:101], v[128:131], off
	s_cmpk_gt_i32 s20, 0x2bff
	s_cbranch_scc0 .Ltc6_win
	s_lshl_b32 s15, s20, 6
	s_lshl_b32 s17, s20, 1
	s_and_b32 s21, s15, 0x7c0
	v_add_u32_e32 v0, s21, v13
	v_ashrrev_i32_e32 v1, 31, v0
	v_lshlrev_b64 v[10:11], 13, v[0:1]
	v_add_u32_e32 v0, s21, v18
	s_and_b32 s24, s17, 0x7c0
	v_ashrrev_i32_e32 v1, 31, v0
	s_cmpk_gt_u32 s20, 0x3bff
	v_lshlrev_b64 v[14:15], 13, v[0:1]
	v_add_u32_e32 v8, s24, v20
	s_cbranch_scc0 .Ltc6_wout
	s_add_i32 s0, s20, 0xffffc400
	s_lshr_b32 s0, s0, 10
	s_lshl_b64 s[4:5], s[0:1], 24
	s_add_u32 s25, s68, s4
	s_addc_u32 s27, s69, s5
	s_lshl_b64 s[4:5], s[0:1], 23
	s_add_u32 s4, s3, s4
	s_addc_u32 s5, s6, s5
	s_branch .Ltc6_sq

.Ltc6_done:
	s_add_i32 s20, s20, s80
	s_waitcnt vmcnt(8)
	s_barrier
	ds_write2_b32 v24, v104, v105 offset1:1
	ds_write2_b32 v24, v106, v107 offset0:2 offset1:3
	ds_write2_b32 v25, v108, v109 offset1:1
	ds_write2_b32 v26, v110, v111 offset1:1
	v_add_u32_e32 v136, 0x400, v114
	v_lshl_add_u64 v[112:113], v[112:113], 0, v[4:5]
	s_waitcnt lgkmcnt(0)
	s_barrier
	ds_read2_b32 v[128:129], v114 offset1:65
	ds_read2_b32 v[130:131], v114 offset0:130 offset1:195
	ds_read2_b32 v[132:133], v136 offset0:4 offset1:69
	ds_read2_b32 v[134:135], v136 offset0:134 offset1:199
	s_waitcnt lgkmcnt(3)
	v_cvt_pk_bf16_f32 v128, v128, v129
	s_waitcnt lgkmcnt(2)
	v_cvt_pk_bf16_f32 v129, v130, v131
	s_waitcnt lgkmcnt(1)
	v_cvt_pk_bf16_f32 v130, v132, v133
	s_waitcnt lgkmcnt(0)
	v_cvt_pk_bf16_f32 v131, v134, v135
	global_store_dwordx4 v[112:113], v[128:131], off
	s_cmpk_gt_i32 s20, 0x2bff
	s_cbranch_scc0 .Ltc7_win
	s_lshl_b32 s15, s20, 6
	s_lshl_b32 s17, s20, 1
	s_and_b32 s21, s15, 0x7c0
	v_add_u32_e32 v0, s21, v13
	v_ashrrev_i32_e32 v1, 31, v0
	v_lshlrev_b64 v[10:11], 13, v[0:1]
	v_add_u32_e32 v0, s21, v18
	s_and_b32 s24, s17, 0x7c0
	v_ashrrev_i32_e32 v1, 31, v0
	s_cmpk_gt_u32 s20, 0x3bff
	v_lshlrev_b64 v[14:15], 13, v[0:1]
	v_add_u32_e32 v8, s24, v20
	s_cbranch_scc0 .Ltc7_wout
	s_add_i32 s0, s20, 0xffffc400
	s_lshr_b32 s0, s0, 10
	s_lshl_b64 s[4:5], s[0:1], 24
	s_add_u32 s25, s68, s4
	s_addc_u32 s27, s69, s5
	s_lshl_b64 s[4:5], s[0:1], 23
	s_add_u32 s4, s3, s4
	s_addc_u32 s5, s6, s5
	s_branch .Ltc7_sq

.Ltc7_done:
	s_add_i32 s20, s20, s80
	s_waitcnt vmcnt(9)
	s_barrier
	ds_write2_b32 v24, v116, v117 offset1:1
	ds_write2_b32 v24, v118, v119 offset0:2 offset1:3
	ds_write2_b32 v25, v120, v121 offset1:1
	ds_write2_b32 v26, v122, v123 offset1:1
	v_add_u32_e32 v136, 0x400, v126
	v_lshl_add_u64 v[124:125], v[124:125], 0, v[4:5]
	s_waitcnt lgkmcnt(0)
	s_barrier
	ds_read2_b32 v[128:129], v126 offset1:65
	ds_read2_b32 v[130:131], v126 offset0:130 offset1:195
	ds_read2_b32 v[132:133], v136 offset0:4 offset1:69
	ds_read2_b32 v[134:135], v136 offset0:134 offset1:199
	s_waitcnt lgkmcnt(3)
	v_cvt_pk_bf16_f32 v128, v128, v129
	s_waitcnt lgkmcnt(2)
	v_cvt_pk_bf16_f32 v129, v130, v131
	s_waitcnt lgkmcnt(1)
	v_cvt_pk_bf16_f32 v130, v132, v133
	s_waitcnt lgkmcnt(0)
	v_cvt_pk_bf16_f32 v131, v134, v135
	global_store_dwordx4 v[124:125], v[128:131], off
	s_movk_i32 s16, 17

.Ltc8_done:
	s_add_i32 s20, s20, s80
	s_waitcnt vmcnt(9)
	s_barrier
	ds_write2_b32 v24, v80, v81 offset1:1
	ds_write2_b32 v24, v82, v83 offset0:2 offset1:3
	ds_write2_b32 v25, v84, v85 offset1:1
	ds_write2_b32 v26, v86, v87 offset1:1
	v_add_u32_e32 v136, 0x400, v90
	v_lshl_add_u64 v[88:89], v[88:89], 0, v[4:5]
	s_waitcnt lgkmcnt(0)
	s_barrier
	ds_read2_b32 v[128:129], v90 offset1:65
	ds_read2_b32 v[130:131], v90 offset0:130 offset1:195
	ds_read2_b32 v[132:133], v136 offset0:4 offset1:69
	ds_read2_b32 v[134:135], v136 offset0:134 offset1:199
	s_waitcnt lgkmcnt(3)
	v_cvt_pk_bf16_f32 v128, v128, v129
	s_waitcnt lgkmcnt(2)
	v_cvt_pk_bf16_f32 v129, v130, v131
	s_waitcnt lgkmcnt(1)
	v_cvt_pk_bf16_f32 v130, v132, v133
	s_waitcnt lgkmcnt(0)
	v_cvt_pk_bf16_f32 v131, v134, v135
	global_store_dwordx4 v[88:89], v[128:131], off
	s_cmpk_gt_i32 s20, 0x2bff
	s_cbranch_scc0 .Ltc9_win
	s_lshl_b32 s15, s20, 6
	s_lshl_b32 s17, s20, 1
	s_and_b32 s21, s15, 0x7c0
	v_add_u32_e32 v0, s21, v13
	v_ashrrev_i32_e32 v1, 31, v0
	v_lshlrev_b64 v[10:11], 13, v[0:1]
	v_add_u32_e32 v0, s21, v18
	s_and_b32 s24, s17, 0x7c0
	v_ashrrev_i32_e32 v1, 31, v0
	s_cmpk_gt_u32 s20, 0x3bff
	v_lshlrev_b64 v[14:15], 13, v[0:1]
	v_add_u32_e32 v8, s24, v20
	s_cbranch_scc0 .Ltc9_wout
	s_add_i32 s0, s20, 0xffffc400
	s_lshr_b32 s0, s0, 10
	s_lshl_b64 s[4:5], s[0:1], 24
	s_add_u32 s25, s68, s4
	s_addc_u32 s27, s69, s5
	s_lshl_b64 s[4:5], s[0:1], 23
	s_add_u32 s4, s3, s4
	s_addc_u32 s5, s6, s5
	s_branch .Ltc9_sq

.Ltc9_done:
	s_add_i32 s20, s20, s80
	s_waitcnt vmcnt(9)
	s_barrier
	ds_write2_b32 v24, v92, v93 offset1:1
	ds_write2_b32 v24, v94, v95 offset0:2 offset1:3
	ds_write2_b32 v25, v96, v97 offset1:1
	ds_write2_b32 v26, v98, v99 offset1:1
	v_add_u32_e32 v136, 0x400, v102
	v_lshl_add_u64 v[100:101], v[100:101], 0, v[4:5]
	s_waitcnt lgkmcnt(0)
	s_barrier
	ds_read2_b32 v[128:129], v102 offset1:65
	ds_read2_b32 v[130:131], v102 offset0:130 offset1:195
	ds_read2_b32 v[132:133], v136 offset0:4 offset1:69
	ds_read2_b32 v[134:135], v136 offset0:134 offset1:199
	s_waitcnt lgkmcnt(3)
	v_cvt_pk_bf16_f32 v128, v128, v129
	s_waitcnt lgkmcnt(2)
	v_cvt_pk_bf16_f32 v129, v130, v131
	s_waitcnt lgkmcnt(1)
	v_cvt_pk_bf16_f32 v130, v132, v133
	s_waitcnt lgkmcnt(0)
	v_cvt_pk_bf16_f32 v131, v134, v135
	global_store_dwordx4 v[100:101], v[128:131], off
	s_cmpk_gt_i32 s20, 0x2bff
	s_cbranch_scc0 .Ltc10_win
	s_lshl_b32 s15, s20, 6
	s_lshl_b32 s17, s20, 1
	s_and_b32 s21, s15, 0x7c0
	v_add_u32_e32 v0, s21, v13
	v_ashrrev_i32_e32 v1, 31, v0
	v_lshlrev_b64 v[10:11], 13, v[0:1]
	v_add_u32_e32 v0, s21, v18
	s_and_b32 s24, s17, 0x7c0
	v_ashrrev_i32_e32 v1, 31, v0
	s_cmpk_gt_u32 s20, 0x3bff
	v_lshlrev_b64 v[14:15], 13, v[0:1]
	v_add_u32_e32 v8, s24, v20
	s_cbranch_scc0 .Ltc10_wout
	s_add_i32 s0, s20, 0xffffc400
	s_lshr_b32 s0, s0, 10
	s_lshl_b64 s[4:5], s[0:1], 24
	s_add_u32 s25, s68, s4
	s_addc_u32 s27, s69, s5
	s_lshl_b64 s[4:5], s[0:1], 23
	s_add_u32 s4, s3, s4
	s_addc_u32 s5, s6, s5
	s_branch .Ltc10_sq

.Ltc10_done:
	s_add_i32 s20, s20, s80
	s_waitcnt vmcnt(9)
	s_barrier
	ds_write2_b32 v24, v104, v105 offset1:1
	ds_write2_b32 v24, v106, v107 offset0:2 offset1:3
	ds_write2_b32 v25, v108, v109 offset1:1
	ds_write2_b32 v26, v110, v111 offset1:1
	v_add_u32_e32 v136, 0x400, v114
	v_lshl_add_u64 v[112:113], v[112:113], 0, v[4:5]
	s_waitcnt lgkmcnt(0)
	s_barrier
	ds_read2_b32 v[128:129], v114 offset1:65
	ds_read2_b32 v[130:131], v114 offset0:130 offset1:195
	ds_read2_b32 v[132:133], v136 offset0:4 offset1:69
	ds_read2_b32 v[134:135], v136 offset0:134 offset1:199
	s_waitcnt lgkmcnt(3)
	v_cvt_pk_bf16_f32 v128, v128, v129
	s_waitcnt lgkmcnt(2)
	v_cvt_pk_bf16_f32 v129, v130, v131
	s_waitcnt lgkmcnt(1)
	v_cvt_pk_bf16_f32 v130, v132, v133
	s_waitcnt lgkmcnt(0)
	v_cvt_pk_bf16_f32 v131, v134, v135
	global_store_dwordx4 v[112:113], v[128:131], off
	s_cmpk_gt_i32 s20, 0x2bff
	s_cbranch_scc0 .Ltc11_win
	s_lshl_b32 s15, s20, 6
	s_lshl_b32 s17, s20, 1
	s_and_b32 s21, s15, 0x7c0
	v_add_u32_e32 v0, s21, v13
	v_ashrrev_i32_e32 v1, 31, v0
	v_lshlrev_b64 v[10:11], 13, v[0:1]
	v_add_u32_e32 v0, s21, v18
	s_and_b32 s24, s17, 0x7c0
	v_ashrrev_i32_e32 v1, 31, v0
	s_cmpk_gt_u32 s20, 0x3bff
	v_lshlrev_b64 v[14:15], 13, v[0:1]
	v_add_u32_e32 v8, s24, v20
	s_cbranch_scc0 .Ltc11_wout
	s_add_i32 s0, s20, 0xffffc400
	s_lshr_b32 s0, s0, 10
	s_lshl_b64 s[4:5], s[0:1], 24
	s_add_u32 s25, s68, s4
	s_addc_u32 s27, s69, s5
	s_lshl_b64 s[4:5], s[0:1], 23
	s_add_u32 s4, s3, s4
	s_addc_u32 s5, s6, s5
	s_branch .Ltc11_sq

.Ltc11_done:
	s_add_i32 s20, s20, s80
	s_waitcnt vmcnt(9)
	s_barrier
	ds_write2_b32 v24, v116, v117 offset1:1
	ds_write2_b32 v24, v118, v119 offset0:2 offset1:3
	ds_write2_b32 v25, v120, v121 offset1:1
	ds_write2_b32 v26, v122, v123 offset1:1
	v_add_u32_e32 v136, 0x400, v126
	v_lshl_add_u64 v[124:125], v[124:125], 0, v[4:5]
	s_waitcnt lgkmcnt(0)
	s_barrier
	ds_read2_b32 v[128:129], v126 offset1:65
	ds_read2_b32 v[130:131], v126 offset0:130 offset1:195
	ds_read2_b32 v[132:133], v136 offset0:4 offset1:69
	ds_read2_b32 v[134:135], v136 offset0:134 offset1:199
	s_waitcnt lgkmcnt(3)
	v_cvt_pk_bf16_f32 v128, v128, v129
	s_waitcnt lgkmcnt(2)
	v_cvt_pk_bf16_f32 v129, v130, v131
	s_waitcnt lgkmcnt(1)
	v_cvt_pk_bf16_f32 v130, v132, v133
	s_waitcnt lgkmcnt(0)
	v_cvt_pk_bf16_f32 v131, v134, v135
	global_store_dwordx4 v[124:125], v[128:131], off
	s_sub_u32 s16, s16, 1
	s_cmp_lg_u32 s16, 0
	s_cbranch_scc1 .Ltc_loop
	s_cmpk_gt_i32 s20, 0x2bff
	s_cbranch_scc0 .Ltc12_win
	s_lshl_b32 s15, s20, 6
	s_lshl_b32 s17, s20, 1
	s_and_b32 s21, s15, 0x7c0
	v_add_u32_e32 v0, s21, v13
	v_ashrrev_i32_e32 v1, 31, v0
	v_lshlrev_b64 v[10:11], 13, v[0:1]
	v_add_u32_e32 v0, s21, v18
	s_and_b32 s24, s17, 0x7c0
	v_ashrrev_i32_e32 v1, 31, v0
	s_cmpk_gt_u32 s20, 0x3bff
	v_lshlrev_b64 v[14:15], 13, v[0:1]
	v_add_u32_e32 v8, s24, v20
	s_cbranch_scc0 .Ltc12_wout
	s_add_i32 s0, s20, 0xffffc400
	s_lshr_b32 s0, s0, 10
	s_lshl_b64 s[4:5], s[0:1], 24
	s_add_u32 s25, s68, s4
	s_addc_u32 s27, s69, s5
	s_lshl_b64 s[4:5], s[0:1], 23
	s_add_u32 s4, s3, s4
	s_addc_u32 s5, s6, s5
	s_branch .Ltc12_sq

.Ltc12_done:
	s_add_i32 s20, s20, s80
	s_waitcnt vmcnt(9)
	s_barrier
	ds_write2_b32 v24, v80, v81 offset1:1
	ds_write2_b32 v24, v82, v83 offset0:2 offset1:3
	ds_write2_b32 v25, v84, v85 offset1:1
	ds_write2_b32 v26, v86, v87 offset1:1
	v_add_u32_e32 v136, 0x400, v90
	v_lshl_add_u64 v[88:89], v[88:89], 0, v[4:5]
	s_waitcnt lgkmcnt(0)
	s_barrier
	ds_read2_b32 v[128:129], v90 offset1:65
	ds_read2_b32 v[130:131], v90 offset0:130 offset1:195
	ds_read2_b32 v[132:133], v136 offset0:4 offset1:69
	ds_read2_b32 v[134:135], v136 offset0:134 offset1:199
	s_waitcnt lgkmcnt(3)
	v_cvt_pk_bf16_f32 v128, v128, v129
	s_waitcnt lgkmcnt(2)
	v_cvt_pk_bf16_f32 v129, v130, v131
	s_waitcnt lgkmcnt(1)
	v_cvt_pk_bf16_f32 v130, v132, v133
	s_waitcnt lgkmcnt(0)
	v_cvt_pk_bf16_f32 v131, v134, v135
	global_store_dwordx4 v[88:89], v[128:131], off
	s_waitcnt vmcnt(7)
	s_barrier
	ds_write2_b32 v24, v92, v93 offset1:1
	ds_write2_b32 v24, v94, v95 offset0:2 offset1:3
	ds_write2_b32 v25, v96, v97 offset1:1
	ds_write2_b32 v26, v98, v99 offset1:1
	v_add_u32_e32 v136, 0x400, v102
	v_lshl_add_u64 v[100:101], v[100:101], 0, v[4:5]
	s_waitcnt lgkmcnt(0)
	s_barrier
	ds_read2_b32 v[128:129], v102 offset1:65
	ds_read2_b32 v[130:131], v102 offset0:130 offset1:195
	ds_read2_b32 v[132:133], v136 offset0:4 offset1:69
	ds_read2_b32 v[134:135], v136 offset0:134 offset1:199
	s_waitcnt lgkmcnt(3)
	v_cvt_pk_bf16_f32 v128, v128, v129
	s_waitcnt lgkmcnt(2)
	v_cvt_pk_bf16_f32 v129, v130, v131
	s_waitcnt lgkmcnt(1)
	v_cvt_pk_bf16_f32 v130, v132, v133
	s_waitcnt lgkmcnt(0)
	v_cvt_pk_bf16_f32 v131, v134, v135
	global_store_dwordx4 v[100:101], v[128:131], off
	s_waitcnt vmcnt(5)
	s_barrier
	ds_write2_b32 v24, v104, v105 offset1:1
	ds_write2_b32 v24, v106, v107 offset0:2 offset1:3
	ds_write2_b32 v25, v108, v109 offset1:1
	ds_write2_b32 v26, v110, v111 offset1:1
	v_add_u32_e32 v136, 0x400, v114
	v_lshl_add_u64 v[112:113], v[112:113], 0, v[4:5]
	s_waitcnt lgkmcnt(0)
	s_barrier
	ds_read2_b32 v[128:129], v114 offset1:65
	ds_read2_b32 v[130:131], v114 offset0:130 offset1:195
	ds_read2_b32 v[132:133], v136 offset0:4 offset1:69
	ds_read2_b32 v[134:135], v136 offset0:134 offset1:199
	s_waitcnt lgkmcnt(3)
	v_cvt_pk_bf16_f32 v128, v128, v129
	s_waitcnt lgkmcnt(2)
	v_cvt_pk_bf16_f32 v129, v130, v131
	s_waitcnt lgkmcnt(1)
	v_cvt_pk_bf16_f32 v130, v132, v133
	s_waitcnt lgkmcnt(0)
	v_cvt_pk_bf16_f32 v131, v134, v135
	global_store_dwordx4 v[112:113], v[128:131], off
	s_waitcnt vmcnt(3)
	s_barrier
	ds_write2_b32 v24, v116, v117 offset1:1
	ds_write2_b32 v24, v118, v119 offset0:2 offset1:3
	ds_write2_b32 v25, v120, v121 offset1:1
	ds_write2_b32 v26, v122, v123 offset1:1
	v_add_u32_e32 v136, 0x400, v126
	v_lshl_add_u64 v[124:125], v[124:125], 0, v[4:5]
	s_waitcnt lgkmcnt(0)
	s_barrier
	ds_read2_b32 v[128:129], v126 offset1:65
	ds_read2_b32 v[130:131], v126 offset0:130 offset1:195
	ds_read2_b32 v[132:133], v136 offset0:4 offset1:69
	ds_read2_b32 v[134:135], v136 offset0:134 offset1:199
	s_waitcnt lgkmcnt(3)
	v_cvt_pk_bf16_f32 v128, v128, v129
	s_waitcnt lgkmcnt(2)
	v_cvt_pk_bf16_f32 v129, v130, v131
	s_waitcnt lgkmcnt(1)
	v_cvt_pk_bf16_f32 v130, v132, v133
	s_waitcnt lgkmcnt(0)
	v_cvt_pk_bf16_f32 v131, v134, v135
	global_store_dwordx4 v[124:125], v[128:131], off
